# route_a prologue: duplicate back-to-back block barrier removed (on top of P7 permlane reductions)
# baseline (speedup 1.0000x reference)
.LBB0_942:
	s_or_b64 exec, exec, s[0:1]
	v_readlane_b32 s4, v248, 40
	v_readlane_b32 s0, v247, 0
	v_readlane_b32 s5, v248, 41
	v_readlane_b32 s6, v248, 42
	v_readlane_b32 s7, v248, 43
	v_readlane_b32 s8, v248, 44
	v_readlane_b32 s9, v248, 45
	s_and_b32 s2, s0, 1
	v_readlane_b32 s10, v248, 46
	v_readlane_b32 s11, v248, 47
	s_mov_b64 s[4:5], s[8:9]
	v_readlane_b32 s1, v247, 1
	s_cmp_eq_u32 s2, 0
	s_mov_b64 s[6:7], s[10:11]
	s_waitcnt vmcnt(5)
	v_add_u32_e32 v4, 0x100, v130
	s_cselect_b32 s1, s5, s7
	s_cselect_b32 s0, s4, s6
	v_mov_b32_e32 v85, 0
	v_lshrrev_b32_e32 v26, 4, v4
	s_waitcnt lgkmcnt(0)
	v_lshl_add_u64 v[0:1], s[0:1], 0, v[84:85]
	v_lshlrev_b32_e32 v2, 1, v159
	v_mov_b32_e32 v3, v85
	v_lshlrev_b32_e32 v4, 8, v26
	v_mov_b32_e32 v5, v85
	v_lshl_add_u64 v[2:3], v[0:1], 0, v[2:3]
	v_lshl_add_u64 v[4:5], v[0:1], 0, v[4:5]
	s_nop 0
	s_barrier
	global_load_dwordx4 v[6:9], v[2:3], off
	global_load_dwordx4 v[10:13], v[4:5], off
	v_add_u32_e32 v2, 0x200, v130
	v_add_u32_e32 v4, 0x300, v130
	v_lshrrev_b32_e32 v27, 4, v2
	v_lshrrev_b32_e32 v28, 4, v4
	v_lshlrev_b32_e32 v2, 8, v27
	v_mov_b32_e32 v3, v85
	v_lshlrev_b32_e32 v4, 8, v28
	v_mov_b32_e32 v5, v85
	v_lshl_add_u64 v[2:3], v[0:1], 0, v[2:3]
	v_lshl_add_u64 v[4:5], v[0:1], 0, v[4:5]
	global_load_dwordx4 v[14:17], v[2:3], off
	global_load_dwordx4 v[18:21], v[4:5], off
	v_or_b32_e32 v5, 0x400, v130
	v_lshrrev_b32_e32 v29, 4, v5
	v_lshlrev_b32_e32 v2, 8, v29
	v_mov_b32_e32 v3, v85
	v_lshl_add_u64 v[2:3], v[0:1], 0, v[2:3]
	global_load_dwordx4 v[22:25], v[2:3], off
	v_add_u32_e32 v42, 0x500, v130
	v_lshrrev_b32_e32 v48, 4, v42
	v_lshlrev_b32_e32 v42, 8, v48
	v_mov_b32_e32 v43, v85
	v_lshl_add_u64 v[42:43], v[0:1], 0, v[42:43]
	global_load_dwordx4 v[30:33], v[42:43], off
	v_mov_b32_e32 v44, 0x6000
	v_lshl_or_b32 v44, v136, 8, v44
	v_mov_b32_e32 v45, v85
	v_lshl_add_u64 v[44:45], v[0:1], 0, v[44:45]
	global_load_dwordx4 v[34:37], v[44:45], off
	v_add_u32_e32 v46, 0x700, v130
	v_lshrrev_b32_e32 v49, 4, v46
	v_lshlrev_b32_e32 v46, 8, v49
	v_mov_b32_e32 v47, v85
	v_lshl_add_u64 v[46:47], v[0:1], 0, v[46:47]
	global_load_dwordx4 v[38:41], v[46:47], off
	s_movk_i32 s4, 0x110
	s_movk_i32 s0, 0x700
	s_movk_i32 s3, 0x200
	v_mad_u32_u24 v4, v136, s4, v84
	v_cmp_gt_u32_e32 vcc, s0, v5
	v_readlane_b32 s12, v248, 48
	v_readlane_b32 s13, v248, 49
	v_readlane_b32 s14, v248, 50
	v_readlane_b32 s15, v248, 51
	v_readlane_b32 s16, v248, 52
	v_readlane_b32 s17, v248, 53
	v_readlane_b32 s18, v248, 54
	v_readlane_b32 s19, v248, 55
	v_mad_u32_u24 v2, v26, s4, v84
	v_mad_u32_u24 v3, v27, s4, v84
	v_mad_u32_u24 v26, v28, s4, v84
	v_mad_u32_u24 v27, v29, s4, v84
	s_waitcnt vmcnt(7)
	ds_write_b128 v4, v[6:9]
	s_waitcnt vmcnt(6)
	ds_write_b128 v2, v[10:13]
	s_waitcnt vmcnt(5)
	ds_write_b128 v3, v[14:17]
	s_waitcnt vmcnt(4)
	ds_write_b128 v26, v[18:21]
	s_waitcnt vmcnt(3)
	ds_write_b128 v27, v[22:25]
	s_and_saveexec_b64 s[0:1], vcc
	s_cbranch_execz .LBB0_946
	v_mad_u32_u24 v48, v48, s4, v84
	v_mad_u32_u24 v49, v49, s4, v84
	s_waitcnt vmcnt(2)
	ds_write_b128 v48, v[30:33]
	s_waitcnt vmcnt(1)
	ds_write_b128 v4, v[34:37] offset:26112
	s_waitcnt vmcnt(0)
	ds_write_b128 v49, v[38:41]
